# v8 + residual GEMM epilogues (X += gate*acc) as an 11-deep rolling load pipeline with counted waits instead of vmcnt(0) after every load
# speedup vs baseline: 1.0045x; 1.0045x over previous
;     __device__ __forceinline__ void operator()(const pg8::f32x4 (&acc)[2][2][4][2], const pg8::Unit& u, int wr, int wc, int fr, int fq) const {
;         const int b = u.pm / 9, j = u.pm - b * 9;
;         float* base = (j == 0) ? xc + (size_t)b * CTX * DM : out + ((size_t)b * SEQ + (size_t)(j - 1) * 256) * DM;
;         const float* g = gate + (size_t)((j == 0) ? 16 : b) * MODW;
;         const int col0 = u.pn * 256 + wc * 32 + 4 * fq;
;         pg8::f32x4 gv[2][2];
; #pragma unroll
;         for (int bj = 0; bj < 2; ++bj)
; #pragma unroll
;             for (int n = 0; n < 2; ++n) gv[bj][n] = *(const pg8::f32x4*)(g + col0 + bj * 128 + n * 16);
; #pragma unroll
;         for (int ai = 0; ai < 2; ++ai)
; #pragma unroll
;             for (int m = 0; m < 4; ++m) {
;                 float* rowp = base + (size_t)(ai * 128 + wr * 64 + m * 16 + fr) * DM + col0;
; #pragma unroll
;                 for (int bj = 0; bj < 2; ++bj)
; #pragma unroll
;                     for (int n = 0; n < 2; ++n) {
;                         pg8::f32x4* p = (pg8::f32x4*)(rowp + bj * 128 + n * 16);
;                         pg8::f32x4 xv = *p; xv = xv + gv[bj][n] * acc[ai][bj][m][n]; *p = xv;
;                     }
;                 if (m & 1) asm volatile("" ::: "memory");
;             }
.LBB0_854:
	s_lshl_b64 s[12:13], s[54:55], 2
	v_lshl_or_b32 v88, s62, 8, v171
	s_add_u32 s12, s41, s12
	v_ashrrev_i32_e32 v89, 31, v88
	s_addc_u32 s13, s0, s13
	v_lshlrev_b64 v[168:169], 2, v[88:89]
	v_lshl_add_u64 v[88:89], s[12:13], 0, v[168:169]
	v_lshl_add_u64 v[168:169], s[50:51], 0, v[168:169]
	v_lshl_add_u64 v[178:179], v[168:169], 0, v[148:149]
	global_load_dwordx4 v[108:111], v[88:89], off
	global_load_dwordx4 v[104:107], v[88:89], off offset:64
	global_load_dwordx4 v[100:103], v[88:89], off offset:512
	s_nop 0
	global_load_dwordx4 v[88:91], v[88:89], off offset:576
	s_mov_b64 s[50:51], -1
	s_andn2_b64 vcc, exec, s[38:39]
	v_lshl_add_u64 v[174:175], v[168:169], 0, v[148:149]
	global_load_dwordx4 v[184:187], v[174:175], off
	global_load_dwordx4 v[188:191], v[174:175], off offset:64
	global_load_dwordx4 v[192:195], v[174:175], off offset:512
	global_load_dwordx4 v[196:199], v[174:175], off offset:576
	v_lshl_add_u64 v[176:177], v[168:169], 0, v[150:151]
	global_load_dwordx4 v[204:207], v[176:177], off
	global_load_dwordx4 v[208:211], v[176:177], off offset:64
	global_load_dwordx4 v[212:215], v[176:177], off offset:512
	global_load_dwordx4 v[216:219], v[176:177], off offset:576
	v_lshl_add_u64 v[178:179], v[168:169], 0, v[152:153]
	global_load_dwordx4 v[220:223], v[178:179], off
	global_load_dwordx4 v[224:227], v[178:179], off offset:64
	global_load_dwordx4 v[228:231], v[178:179], off offset:512
	s_waitcnt vmcnt(10)
	v_pk_fma_f32 v[186:187], v[144:145], v[110:111], v[186:187]
	v_pk_fma_f32 v[184:185], v[142:143], v[108:109], v[184:185]
	global_store_dwordx4 v[174:175], v[184:187], off
	s_nop 0
	global_load_dwordx4 v[184:187], v[178:179], off offset:576
	s_waitcnt vmcnt(11)
	v_pk_fma_f32 v[190:191], v[140:141], v[106:107], v[190:191]
	v_pk_fma_f32 v[188:189], v[138:139], v[104:105], v[188:189]
	global_store_dwordx4 v[174:175], v[188:191], off offset:64
	s_nop 0
	v_lshl_add_u64 v[180:181], v[168:169], 0, v[154:155]
	global_load_dwordx4 v[188:191], v[180:181], off
	s_waitcnt vmcnt(12)
	v_pk_fma_f32 v[194:195], v[136:137], v[102:103], v[194:195]
	v_pk_fma_f32 v[192:193], v[134:135], v[100:101], v[192:193]
	global_store_dwordx4 v[174:175], v[192:195], off offset:512
	s_nop 0
	global_load_dwordx4 v[192:195], v[180:181], off offset:64
	s_waitcnt vmcnt(13)
	v_pk_fma_f32 v[198:199], v[126:127], v[90:91], v[198:199]
	v_pk_fma_f32 v[196:197], v[124:125], v[88:89], v[196:197]
	global_store_dwordx4 v[174:175], v[196:199], off offset:576
	s_nop 0
	global_load_dwordx4 v[196:199], v[180:181], off offset:512
	s_waitcnt vmcnt(14)
	v_pk_fma_f32 v[206:207], v[132:133], v[110:111], v[206:207]
	v_pk_fma_f32 v[204:205], v[130:131], v[108:109], v[204:205]
	global_store_dwordx4 v[176:177], v[204:207], off
	s_nop 0
	global_load_dwordx4 v[204:207], v[180:181], off offset:576
	s_waitcnt vmcnt(15)
	v_pk_fma_f32 v[210:211], v[122:123], v[106:107], v[210:211]
	v_pk_fma_f32 v[208:209], v[120:121], v[104:105], v[208:209]
	global_store_dwordx4 v[176:177], v[208:211], off offset:64
	s_nop 0
	v_lshl_add_u64 v[174:175], v[168:169], 0, v[156:157]
	global_load_dwordx4 v[208:211], v[174:175], off
	s_waitcnt vmcnt(16)
	v_pk_fma_f32 v[214:215], v[118:119], v[102:103], v[214:215]
	v_pk_fma_f32 v[212:213], v[116:117], v[100:101], v[212:213]
	global_store_dwordx4 v[176:177], v[212:215], off offset:512
	s_nop 0
	global_load_dwordx4 v[212:215], v[174:175], off offset:64
	s_waitcnt vmcnt(17)
	v_pk_fma_f32 v[218:219], v[114:115], v[90:91], v[218:219]
	v_pk_fma_f32 v[216:217], v[112:113], v[88:89], v[216:217]
	global_store_dwordx4 v[176:177], v[216:219], off offset:576
	s_nop 0
	global_load_dwordx4 v[216:219], v[174:175], off offset:512
	s_waitcnt vmcnt(18)
	v_pk_fma_f32 v[222:223], v[98:99], v[110:111], v[222:223]
	v_pk_fma_f32 v[220:221], v[96:97], v[108:109], v[220:221]
	global_store_dwordx4 v[178:179], v[220:223], off
	s_nop 0
	global_load_dwordx4 v[220:223], v[174:175], off offset:576
	s_waitcnt vmcnt(19)
	v_pk_fma_f32 v[226:227], v[94:95], v[106:107], v[226:227]
	v_pk_fma_f32 v[224:225], v[92:93], v[104:105], v[224:225]
	global_store_dwordx4 v[178:179], v[224:227], off offset:64
	s_nop 0
	v_lshl_add_u64 v[176:177], v[168:169], 0, v[158:159]
	global_load_dwordx4 v[224:227], v[176:177], off
	s_waitcnt vmcnt(20)
	v_pk_fma_f32 v[230:231], v[86:87], v[102:103], v[230:231]
	v_pk_fma_f32 v[228:229], v[84:85], v[100:101], v[228:229]
	global_store_dwordx4 v[178:179], v[228:231], off offset:512
	s_nop 0
	global_load_dwordx4 v[228:231], v[176:177], off offset:64
	s_waitcnt vmcnt(20)
	v_pk_fma_f32 v[186:187], v[78:79], v[90:91], v[186:187]
	v_pk_fma_f32 v[184:185], v[76:77], v[88:89], v[184:185]
	global_store_dwordx4 v[178:179], v[184:187], off offset:576
	s_nop 0
	global_load_dwordx4 v[184:187], v[176:177], off offset:512
	s_waitcnt vmcnt(20)
; #define PG8_BAR __builtin_amdgcn_s_barrier()
; template <class Epi, class Sched, bool ALIGN_EPI = false, bool SP2 = false>
; __device__ __forceinline__ void gemm_phase(PG8_LAS unsigned char* lds, const Gemm g, const Sched& S, const Epi& E) {
;     ...
;         if (!has_next) break;
; #pragma unroll
;         for (int a = 0; a < 2; ++a)
; #pragma unroll
;             for (int b = 0; b < 2; ++b)
; #pragma unroll
;                 for (int m = 0; m < 4; ++m)
; #pragma unroll
;                     for (int n = 0; n < 2; ++n) acc[a][b][m][n] = (f32x4){0.f, 0.f, 0.f, 0.f};
;         cur = nxt; cA = nA; cB = nB; ++ui;
;         if constexpr (ALIGN_EPI) { if (wr == 1) PG8_BAR; }
;     __device__ __forceinline__ void operator()(const pg8::f32x4 (&acc)[2][2][4][2], const pg8::Unit& u, int wr, int wc, int fr, int fq) const {
;     ...
; #pragma unroll
;         for (int ai = 0; ai < 2; ++ai)
; #pragma unroll
;             for (int m = 0; m < 4; ++m) {
;                 float* rowp = base + (size_t)(ai * 128 + wr * 64 + m * 16 + fr) * DM + col0;
; #pragma unroll
;                 for (int bj = 0; bj < 2; ++bj)
; #pragma unroll
;                     for (int n = 0; n < 2; ++n) {
;                         pg8::f32x4* p = (pg8::f32x4*)(rowp + bj * 128 + n * 16);
;                         pg8::f32x4 xv = *p; xv = xv + gv[bj][n] * acc[ai][bj][m][n]; *p = xv;
;                     }
;                 if (m & 1) asm volatile("" ::: "memory");
;             }
	v_pk_fma_f32 v[190:191], v[82:83], v[110:111], v[190:191]
	v_pk_fma_f32 v[188:189], v[80:81], v[108:109], v[188:189]
	global_store_dwordx4 v[180:181], v[188:191], off
	s_nop 0
	global_load_dwordx4 v[188:191], v[176:177], off offset:576
	s_waitcnt vmcnt(20)
	v_pk_fma_f32 v[194:195], v[74:75], v[106:107], v[194:195]
	v_pk_fma_f32 v[192:193], v[72:73], v[104:105], v[192:193]
	global_store_dwordx4 v[180:181], v[192:195], off offset:64
	s_nop 0
	v_lshl_add_u64 v[178:179], v[168:169], 0, v[160:161]
	global_load_dwordx4 v[192:195], v[178:179], off
	s_waitcnt vmcnt(20)
	v_pk_fma_f32 v[198:199], v[70:71], v[102:103], v[198:199]
	v_pk_fma_f32 v[196:197], v[68:69], v[100:101], v[196:197]
	global_store_dwordx4 v[180:181], v[196:199], off offset:512
	s_nop 0
	global_load_dwordx4 v[196:199], v[178:179], off offset:64
	s_waitcnt vmcnt(20)
	v_pk_fma_f32 v[206:207], v[66:67], v[90:91], v[206:207]
	v_pk_fma_f32 v[204:205], v[64:65], v[88:89], v[204:205]
	global_store_dwordx4 v[180:181], v[204:207], off offset:576
	s_nop 0
	global_load_dwordx4 v[204:207], v[178:179], off offset:512
	s_waitcnt vmcnt(20)
	v_pk_fma_f32 v[210:211], v[62:63], v[110:111], v[210:211]
	v_pk_fma_f32 v[208:209], v[60:61], v[108:109], v[208:209]
	global_store_dwordx4 v[174:175], v[208:211], off
	s_nop 0
	global_load_dwordx4 v[208:211], v[178:179], off offset:576
	s_waitcnt vmcnt(20)
	v_pk_fma_f32 v[214:215], v[58:59], v[106:107], v[214:215]
	v_pk_fma_f32 v[212:213], v[56:57], v[104:105], v[212:213]
	global_store_dwordx4 v[174:175], v[212:215], off offset:64
	s_nop 0
	v_lshl_add_u64 v[180:181], v[168:169], 0, v[162:163]
	global_load_dwordx4 v[212:215], v[180:181], off
	s_waitcnt vmcnt(20)
	v_pk_fma_f32 v[218:219], v[54:55], v[102:103], v[218:219]
	v_pk_fma_f32 v[216:217], v[52:53], v[100:101], v[216:217]
	global_store_dwordx4 v[174:175], v[216:219], off offset:512
	s_nop 0
	global_load_dwordx4 v[216:219], v[180:181], off offset:64
	s_waitcnt vmcnt(20)
	v_pk_fma_f32 v[222:223], v[46:47], v[90:91], v[222:223]
	v_pk_fma_f32 v[220:221], v[44:45], v[88:89], v[220:221]
	global_store_dwordx4 v[174:175], v[220:223], off offset:576
	s_nop 0
	global_load_dwordx4 v[220:223], v[180:181], off offset:512
	s_waitcnt vmcnt(20)
	v_pk_fma_f32 v[226:227], v[50:51], v[110:111], v[226:227]
	v_pk_fma_f32 v[224:225], v[48:49], v[108:109], v[224:225]
	global_store_dwordx4 v[176:177], v[224:227], off
	s_nop 0
	global_load_dwordx4 v[224:227], v[180:181], off offset:576
	s_waitcnt vmcnt(20)
	v_pk_fma_f32 v[230:231], v[42:43], v[106:107], v[230:231]
	v_pk_fma_f32 v[228:229], v[40:41], v[104:105], v[228:229]
	global_store_dwordx4 v[176:177], v[228:231], off offset:64
	s_waitcnt vmcnt(19)
	v_pk_fma_f32 v[186:187], v[38:39], v[102:103], v[186:187]
	v_pk_fma_f32 v[184:185], v[36:37], v[100:101], v[184:185]
	global_store_dwordx4 v[176:177], v[184:187], off offset:512
	s_waitcnt vmcnt(18)
	v_pk_fma_f32 v[190:191], v[34:35], v[90:91], v[190:191]
	v_pk_fma_f32 v[188:189], v[32:33], v[88:89], v[188:189]
	global_store_dwordx4 v[176:177], v[188:191], off offset:576
	s_waitcnt vmcnt(17)
	v_pk_fma_f32 v[194:195], v[30:31], v[110:111], v[194:195]
	v_pk_fma_f32 v[192:193], v[28:29], v[108:109], v[192:193]
	global_store_dwordx4 v[178:179], v[192:195], off
	s_waitcnt vmcnt(16)
	v_pk_fma_f32 v[198:199], v[26:27], v[106:107], v[198:199]
	v_pk_fma_f32 v[196:197], v[24:25], v[104:105], v[196:197]
	global_store_dwordx4 v[178:179], v[196:199], off offset:64
	s_waitcnt vmcnt(15)
	v_pk_fma_f32 v[206:207], v[22:23], v[102:103], v[206:207]
	v_pk_fma_f32 v[204:205], v[20:21], v[100:101], v[204:205]
	global_store_dwordx4 v[178:179], v[204:207], off offset:512
	s_waitcnt vmcnt(14)
	v_pk_fma_f32 v[210:211], v[14:15], v[90:91], v[210:211]
	v_pk_fma_f32 v[208:209], v[12:13], v[88:89], v[208:209]
	global_store_dwordx4 v[178:179], v[208:211], off offset:576
	s_waitcnt vmcnt(13)
	v_pk_fma_f32 v[214:215], v[18:19], v[110:111], v[214:215]
	v_pk_fma_f32 v[212:213], v[16:17], v[108:109], v[212:213]
	global_store_dwordx4 v[180:181], v[212:215], off
	s_waitcnt vmcnt(12)
	v_pk_fma_f32 v[218:219], v[10:11], v[106:107], v[218:219]
	v_pk_fma_f32 v[216:217], v[8:9], v[104:105], v[216:217]
	global_store_dwordx4 v[180:181], v[216:219], off offset:64
	s_waitcnt vmcnt(11)
	v_pk_fma_f32 v[222:223], v[6:7], v[102:103], v[222:223]
	v_pk_fma_f32 v[220:221], v[4:5], v[100:101], v[220:221]
	global_store_dwordx4 v[180:181], v[220:223], off offset:512
	s_waitcnt vmcnt(10)
	v_pk_fma_f32 v[226:227], v[2:3], v[90:91], v[226:227]
	v_pk_fma_f32 v[224:225], v[0:1], v[88:89], v[224:225]
	global_store_dwordx4 v[180:181], v[224:227], off offset:576
	s_cbranch_vccnz .LBB0_844
	s_andn2_b64 vcc, exec, s[10:11]
	s_cbranch_vccnz .LBB0_843
	s_barrier
	s_branch .LBB0_843

;     __device__ __forceinline__ void operator()(const pg8::f32x4 (&acc)[2][2][4][2], const pg8::Unit& u, int wr, int wc, int fr, int fq) const {
;         const int b = u.pm / 9, j = u.pm - b * 9;
;         float* base = (j == 0) ? xc + (size_t)b * CTX * DM : out + ((size_t)b * SEQ + (size_t)(j - 1) * 256) * DM;
;         const float* g = gate + (size_t)((j == 0) ? 16 : b) * MODW;
;         const int col0 = u.pn * 256 + wc * 32 + 4 * fq;
;         pg8::f32x4 gv[2][2];
; #pragma unroll
;         for (int bj = 0; bj < 2; ++bj)
; #pragma unroll
;             for (int n = 0; n < 2; ++n) gv[bj][n] = *(const pg8::f32x4*)(g + col0 + bj * 128 + n * 16);
; #pragma unroll
;         for (int ai = 0; ai < 2; ++ai)
; #pragma unroll
;             for (int m = 0; m < 4; ++m) {
;                 float* rowp = base + (size_t)(ai * 128 + wr * 64 + m * 16 + fr) * DM + col0;
; #pragma unroll
;                 for (int bj = 0; bj < 2; ++bj)
; #pragma unroll
;                     for (int n = 0; n < 2; ++n) {
;                         pg8::f32x4* p = (pg8::f32x4*)(rowp + bj * 128 + n * 16);
;                         pg8::f32x4 xv = *p; xv = xv + gv[bj][n] * acc[ai][bj][m][n]; *p = xv;
;                     }
;                 if (m & 1) asm volatile("" ::: "memory");
;             }
.LBB0_880:
	s_lshl_b64 s[12:13], s[56:57], 2
	v_lshl_or_b32 v88, s62, 8, v171
	s_add_u32 s12, s41, s12
	v_ashrrev_i32_e32 v89, 31, v88
	s_addc_u32 s13, s0, s13
	v_lshlrev_b64 v[168:169], 2, v[88:89]
	v_lshl_add_u64 v[88:89], s[12:13], 0, v[168:169]
	v_lshl_add_u64 v[168:169], s[52:53], 0, v[168:169]
	v_lshl_add_u64 v[178:179], v[168:169], 0, v[148:149]
	global_load_dwordx4 v[108:111], v[88:89], off
	global_load_dwordx4 v[104:107], v[88:89], off offset:64
	global_load_dwordx4 v[100:103], v[88:89], off offset:512
	s_nop 0
	global_load_dwordx4 v[88:91], v[88:89], off offset:576
	s_mov_b64 s[52:53], -1
	s_andn2_b64 vcc, exec, s[42:43]
	v_lshl_add_u64 v[174:175], v[168:169], 0, v[148:149]
	global_load_dwordx4 v[184:187], v[174:175], off
	global_load_dwordx4 v[188:191], v[174:175], off offset:64
	global_load_dwordx4 v[192:195], v[174:175], off offset:512
	global_load_dwordx4 v[196:199], v[174:175], off offset:576
	v_lshl_add_u64 v[176:177], v[168:169], 0, v[150:151]
	global_load_dwordx4 v[204:207], v[176:177], off
	global_load_dwordx4 v[208:211], v[176:177], off offset:64
	global_load_dwordx4 v[212:215], v[176:177], off offset:512
	global_load_dwordx4 v[216:219], v[176:177], off offset:576
	v_lshl_add_u64 v[178:179], v[168:169], 0, v[152:153]
	global_load_dwordx4 v[220:223], v[178:179], off
	global_load_dwordx4 v[224:227], v[178:179], off offset:64
	global_load_dwordx4 v[228:231], v[178:179], off offset:512
	s_waitcnt vmcnt(10)
	v_pk_fma_f32 v[186:187], v[144:145], v[110:111], v[186:187]
	v_pk_fma_f32 v[184:185], v[142:143], v[108:109], v[184:185]
	global_store_dwordx4 v[174:175], v[184:187], off
	s_nop 0
	global_load_dwordx4 v[184:187], v[178:179], off offset:576
	s_waitcnt vmcnt(11)
	v_pk_fma_f32 v[190:191], v[140:141], v[106:107], v[190:191]
	v_pk_fma_f32 v[188:189], v[138:139], v[104:105], v[188:189]
	global_store_dwordx4 v[174:175], v[188:191], off offset:64
	s_nop 0
	v_lshl_add_u64 v[180:181], v[168:169], 0, v[154:155]
	global_load_dwordx4 v[188:191], v[180:181], off
	s_waitcnt vmcnt(12)
	v_pk_fma_f32 v[194:195], v[136:137], v[102:103], v[194:195]
	v_pk_fma_f32 v[192:193], v[134:135], v[100:101], v[192:193]
	global_store_dwordx4 v[174:175], v[192:195], off offset:512
	s_nop 0
	global_load_dwordx4 v[192:195], v[180:181], off offset:64
	s_waitcnt vmcnt(13)
	v_pk_fma_f32 v[198:199], v[126:127], v[90:91], v[198:199]
	v_pk_fma_f32 v[196:197], v[124:125], v[88:89], v[196:197]
	global_store_dwordx4 v[174:175], v[196:199], off offset:576
	s_nop 0
	global_load_dwordx4 v[196:199], v[180:181], off offset:512
	s_waitcnt vmcnt(14)
	v_pk_fma_f32 v[206:207], v[132:133], v[110:111], v[206:207]
	v_pk_fma_f32 v[204:205], v[130:131], v[108:109], v[204:205]
	global_store_dwordx4 v[176:177], v[204:207], off
	s_nop 0
	global_load_dwordx4 v[204:207], v[180:181], off offset:576
	s_waitcnt vmcnt(15)
	v_pk_fma_f32 v[210:211], v[122:123], v[106:107], v[210:211]
	v_pk_fma_f32 v[208:209], v[120:121], v[104:105], v[208:209]
	global_store_dwordx4 v[176:177], v[208:211], off offset:64
	s_nop 0
	v_lshl_add_u64 v[174:175], v[168:169], 0, v[156:157]
	global_load_dwordx4 v[208:211], v[174:175], off
	s_waitcnt vmcnt(16)
	v_pk_fma_f32 v[214:215], v[118:119], v[102:103], v[214:215]
	v_pk_fma_f32 v[212:213], v[116:117], v[100:101], v[212:213]
	global_store_dwordx4 v[176:177], v[212:215], off offset:512
	s_nop 0
	global_load_dwordx4 v[212:215], v[174:175], off offset:64
	s_waitcnt vmcnt(17)
	v_pk_fma_f32 v[218:219], v[114:115], v[90:91], v[218:219]
	v_pk_fma_f32 v[216:217], v[112:113], v[88:89], v[216:217]
	global_store_dwordx4 v[176:177], v[216:219], off offset:576
	s_nop 0
	global_load_dwordx4 v[216:219], v[174:175], off offset:512
	s_waitcnt vmcnt(18)
	v_pk_fma_f32 v[222:223], v[98:99], v[110:111], v[222:223]
	v_pk_fma_f32 v[220:221], v[96:97], v[108:109], v[220:221]
	global_store_dwordx4 v[178:179], v[220:223], off
	s_nop 0
	global_load_dwordx4 v[220:223], v[174:175], off offset:576
	s_waitcnt vmcnt(19)
	v_pk_fma_f32 v[226:227], v[94:95], v[106:107], v[226:227]
	v_pk_fma_f32 v[224:225], v[92:93], v[104:105], v[224:225]
	global_store_dwordx4 v[178:179], v[224:227], off offset:64
	s_nop 0
	v_lshl_add_u64 v[176:177], v[168:169], 0, v[158:159]
	global_load_dwordx4 v[224:227], v[176:177], off
	s_waitcnt vmcnt(20)
	v_pk_fma_f32 v[230:231], v[86:87], v[102:103], v[230:231]
	v_pk_fma_f32 v[228:229], v[84:85], v[100:101], v[228:229]
	global_store_dwordx4 v[178:179], v[228:231], off offset:512
	s_nop 0
	global_load_dwordx4 v[228:231], v[176:177], off offset:64
	s_waitcnt vmcnt(20)
	v_pk_fma_f32 v[186:187], v[78:79], v[90:91], v[186:187]
	v_pk_fma_f32 v[184:185], v[76:77], v[88:89], v[184:185]
	global_store_dwordx4 v[178:179], v[184:187], off offset:576
	s_nop 0
	global_load_dwordx4 v[184:187], v[176:177], off offset:512
	s_waitcnt vmcnt(20)
;     __device__ __forceinline__ void operator()(const pg8::f32x4 (&acc)[2][2][4][2], const pg8::Unit& u, int wr, int wc, int fr, int fq) const {
;     ...
;         for (int ai = 0; ai < 2; ++ai)
; #pragma unroll
;             for (int m = 0; m < 4; ++m) {
;                 float* rowp = base + (size_t)(ai * 128 + wr * 64 + m * 16 + fr) * DM + col0;
; #pragma unroll
;                 for (int bj = 0; bj < 2; ++bj)
; #pragma unroll
;                     for (int n = 0; n < 2; ++n) {
;                         pg8::f32x4* p = (pg8::f32x4*)(rowp + bj * 128 + n * 16);
;                         pg8::f32x4 xv = *p; xv = xv + gv[bj][n] * acc[ai][bj][m][n]; *p = xv;
;                     }
;                 if (m & 1) asm volatile("" ::: "memory");
;             }
	v_pk_fma_f32 v[190:191], v[82:83], v[110:111], v[190:191]
	v_pk_fma_f32 v[188:189], v[80:81], v[108:109], v[188:189]
	global_store_dwordx4 v[180:181], v[188:191], off
	s_nop 0
	global_load_dwordx4 v[188:191], v[176:177], off offset:576
	s_waitcnt vmcnt(20)
	v_pk_fma_f32 v[194:195], v[74:75], v[106:107], v[194:195]
	v_pk_fma_f32 v[192:193], v[72:73], v[104:105], v[192:193]
	global_store_dwordx4 v[180:181], v[192:195], off offset:64
	s_nop 0
	v_lshl_add_u64 v[178:179], v[168:169], 0, v[160:161]
	global_load_dwordx4 v[192:195], v[178:179], off
	s_waitcnt vmcnt(20)
	v_pk_fma_f32 v[198:199], v[70:71], v[102:103], v[198:199]
	v_pk_fma_f32 v[196:197], v[68:69], v[100:101], v[196:197]
	global_store_dwordx4 v[180:181], v[196:199], off offset:512
	s_nop 0
	global_load_dwordx4 v[196:199], v[178:179], off offset:64
	s_waitcnt vmcnt(20)
	v_pk_fma_f32 v[206:207], v[66:67], v[90:91], v[206:207]
	v_pk_fma_f32 v[204:205], v[64:65], v[88:89], v[204:205]
	global_store_dwordx4 v[180:181], v[204:207], off offset:576
	s_nop 0
	global_load_dwordx4 v[204:207], v[178:179], off offset:512
	s_waitcnt vmcnt(20)
	v_pk_fma_f32 v[210:211], v[62:63], v[110:111], v[210:211]
	v_pk_fma_f32 v[208:209], v[60:61], v[108:109], v[208:209]
	global_store_dwordx4 v[174:175], v[208:211], off
	s_nop 0
	global_load_dwordx4 v[208:211], v[178:179], off offset:576
	s_waitcnt vmcnt(20)
	v_pk_fma_f32 v[214:215], v[58:59], v[106:107], v[214:215]
	v_pk_fma_f32 v[212:213], v[56:57], v[104:105], v[212:213]
	global_store_dwordx4 v[174:175], v[212:215], off offset:64
	s_nop 0
	v_lshl_add_u64 v[180:181], v[168:169], 0, v[162:163]
	global_load_dwordx4 v[212:215], v[180:181], off
	s_waitcnt vmcnt(20)
	v_pk_fma_f32 v[218:219], v[54:55], v[102:103], v[218:219]
	v_pk_fma_f32 v[216:217], v[52:53], v[100:101], v[216:217]
	global_store_dwordx4 v[174:175], v[216:219], off offset:512
	s_nop 0
	global_load_dwordx4 v[216:219], v[180:181], off offset:64
	s_waitcnt vmcnt(20)
	v_pk_fma_f32 v[222:223], v[46:47], v[90:91], v[222:223]
	v_pk_fma_f32 v[220:221], v[44:45], v[88:89], v[220:221]
	global_store_dwordx4 v[174:175], v[220:223], off offset:576
	s_nop 0
	global_load_dwordx4 v[220:223], v[180:181], off offset:512
	s_waitcnt vmcnt(20)
	v_pk_fma_f32 v[226:227], v[50:51], v[110:111], v[226:227]
	v_pk_fma_f32 v[224:225], v[48:49], v[108:109], v[224:225]
	global_store_dwordx4 v[176:177], v[224:227], off
	s_nop 0
	global_load_dwordx4 v[224:227], v[180:181], off offset:576
	s_waitcnt vmcnt(20)
	v_pk_fma_f32 v[230:231], v[42:43], v[106:107], v[230:231]
	v_pk_fma_f32 v[228:229], v[40:41], v[104:105], v[228:229]
	global_store_dwordx4 v[176:177], v[228:231], off offset:64
	s_waitcnt vmcnt(19)
	v_pk_fma_f32 v[186:187], v[38:39], v[102:103], v[186:187]
	v_pk_fma_f32 v[184:185], v[36:37], v[100:101], v[184:185]
	global_store_dwordx4 v[176:177], v[184:187], off offset:512
	s_waitcnt vmcnt(18)
	v_pk_fma_f32 v[190:191], v[34:35], v[90:91], v[190:191]
	v_pk_fma_f32 v[188:189], v[32:33], v[88:89], v[188:189]
	global_store_dwordx4 v[176:177], v[188:191], off offset:576
	s_waitcnt vmcnt(17)
	v_pk_fma_f32 v[194:195], v[30:31], v[110:111], v[194:195]
	v_pk_fma_f32 v[192:193], v[28:29], v[108:109], v[192:193]
	global_store_dwordx4 v[178:179], v[192:195], off
	s_waitcnt vmcnt(16)
	v_pk_fma_f32 v[198:199], v[26:27], v[106:107], v[198:199]
	v_pk_fma_f32 v[196:197], v[24:25], v[104:105], v[196:197]
	global_store_dwordx4 v[178:179], v[196:199], off offset:64
	s_waitcnt vmcnt(15)
	v_pk_fma_f32 v[206:207], v[22:23], v[102:103], v[206:207]
	v_pk_fma_f32 v[204:205], v[20:21], v[100:101], v[204:205]
	global_store_dwordx4 v[178:179], v[204:207], off offset:512
	s_waitcnt vmcnt(14)
	v_pk_fma_f32 v[210:211], v[14:15], v[90:91], v[210:211]
	v_pk_fma_f32 v[208:209], v[12:13], v[88:89], v[208:209]
	global_store_dwordx4 v[178:179], v[208:211], off offset:576
	s_waitcnt vmcnt(13)
	v_pk_fma_f32 v[214:215], v[18:19], v[110:111], v[214:215]
	v_pk_fma_f32 v[212:213], v[16:17], v[108:109], v[212:213]
	global_store_dwordx4 v[180:181], v[212:215], off
	s_waitcnt vmcnt(12)
	v_pk_fma_f32 v[218:219], v[10:11], v[106:107], v[218:219]
	v_pk_fma_f32 v[216:217], v[8:9], v[104:105], v[216:217]
	global_store_dwordx4 v[180:181], v[216:219], off offset:64
	s_waitcnt vmcnt(11)
	v_pk_fma_f32 v[222:223], v[6:7], v[102:103], v[222:223]
	v_pk_fma_f32 v[220:221], v[4:5], v[100:101], v[220:221]
	global_store_dwordx4 v[180:181], v[220:223], off offset:512
	s_waitcnt vmcnt(10)
	v_pk_fma_f32 v[226:227], v[2:3], v[90:91], v[226:227]
	v_pk_fma_f32 v[224:225], v[0:1], v[88:89], v[224:225]
	global_store_dwordx4 v[180:181], v[224:227], off offset:576
	s_cbranch_vccnz .LBB0_866
	s_andn2_b64 vcc, exec, s[10:11]
	s_cbranch_vccnz .LBB0_865
	s_barrier
	s_branch .LBB0_865

;     __device__ __forceinline__ void operator()(const pg8::f32x4 (&acc)[2][2][4][2], const pg8::Unit& u, int wr, int wc, int fr, int fq) const {
;         const int b = u.pm / 9, j = u.pm - b * 9;
;         float* base = (j == 0) ? xc + (size_t)b * CTX * DM : out + ((size_t)b * SEQ + (size_t)(j - 1) * 256) * DM;
;         const float* g = gate + (size_t)((j == 0) ? 16 : b) * MODW;
;         const int col0 = u.pn * 256 + wc * 32 + 4 * fq;
;         pg8::f32x4 gv[2][2];
; #pragma unroll
;         for (int bj = 0; bj < 2; ++bj)
; #pragma unroll
;             for (int n = 0; n < 2; ++n) gv[bj][n] = *(const pg8::f32x4*)(g + col0 + bj * 128 + n * 16);
; #pragma unroll
;         for (int ai = 0; ai < 2; ++ai)
; #pragma unroll
;             for (int m = 0; m < 4; ++m) {
;                 float* rowp = base + (size_t)(ai * 128 + wr * 64 + m * 16 + fr) * DM + col0;
; #pragma unroll
;                 for (int bj = 0; bj < 2; ++bj)
; #pragma unroll
;                     for (int n = 0; n < 2; ++n) {
;                         pg8::f32x4* p = (pg8::f32x4*)(rowp + bj * 128 + n * 16);
;                         pg8::f32x4 xv = *p; xv = xv + gv[bj][n] * acc[ai][bj][m][n]; *p = xv;
;                     }
;                 if (m & 1) asm volatile("" ::: "memory");
;             }
.LBB0_1099:
	s_lshl_b64 s[12:13], s[58:59], 2
	v_lshl_or_b32 v88, s62, 8, v171
	s_add_u32 s12, s11, s12
	v_ashrrev_i32_e32 v89, 31, v88
	s_addc_u32 s13, s24, s13
	v_lshlrev_b64 v[168:169], 2, v[88:89]
	v_lshl_add_u64 v[88:89], s[12:13], 0, v[168:169]
	v_lshl_add_u64 v[168:169], s[50:51], 0, v[168:169]
	v_lshl_add_u64 v[178:179], v[168:169], 0, v[148:149]
	global_load_dwordx4 v[108:111], v[88:89], off
	global_load_dwordx4 v[104:107], v[88:89], off offset:64
	global_load_dwordx4 v[100:103], v[88:89], off offset:512
	s_nop 0
	global_load_dwordx4 v[88:91], v[88:89], off offset:576
	s_mov_b64 s[50:51], -1
	s_and_b64 vcc, exec, s[40:41]
	v_lshl_add_u64 v[174:175], v[168:169], 0, v[148:149]
	global_load_dwordx4 v[184:187], v[174:175], off
	global_load_dwordx4 v[188:191], v[174:175], off offset:64
	global_load_dwordx4 v[192:195], v[174:175], off offset:512
	global_load_dwordx4 v[196:199], v[174:175], off offset:576
	v_lshl_add_u64 v[176:177], v[168:169], 0, v[150:151]
	global_load_dwordx4 v[204:207], v[176:177], off
	global_load_dwordx4 v[208:211], v[176:177], off offset:64
	global_load_dwordx4 v[212:215], v[176:177], off offset:512
	global_load_dwordx4 v[216:219], v[176:177], off offset:576
	v_lshl_add_u64 v[178:179], v[168:169], 0, v[152:153]
	global_load_dwordx4 v[220:223], v[178:179], off
	global_load_dwordx4 v[224:227], v[178:179], off offset:64
	global_load_dwordx4 v[228:231], v[178:179], off offset:512
	s_waitcnt vmcnt(10)
	v_pk_fma_f32 v[186:187], v[144:145], v[110:111], v[186:187]
	v_pk_fma_f32 v[184:185], v[142:143], v[108:109], v[184:185]
	global_store_dwordx4 v[174:175], v[184:187], off
	s_nop 0
	global_load_dwordx4 v[184:187], v[178:179], off offset:576
	s_waitcnt vmcnt(11)
	v_pk_fma_f32 v[190:191], v[140:141], v[106:107], v[190:191]
	v_pk_fma_f32 v[188:189], v[138:139], v[104:105], v[188:189]
	global_store_dwordx4 v[174:175], v[188:191], off offset:64
	s_nop 0
	v_lshl_add_u64 v[180:181], v[168:169], 0, v[154:155]
	global_load_dwordx4 v[188:191], v[180:181], off
	s_waitcnt vmcnt(12)
	v_pk_fma_f32 v[194:195], v[136:137], v[102:103], v[194:195]
	v_pk_fma_f32 v[192:193], v[134:135], v[100:101], v[192:193]
	global_store_dwordx4 v[174:175], v[192:195], off offset:512
	s_nop 0
	global_load_dwordx4 v[192:195], v[180:181], off offset:64
	s_waitcnt vmcnt(13)
	v_pk_fma_f32 v[198:199], v[126:127], v[90:91], v[198:199]
	v_pk_fma_f32 v[196:197], v[124:125], v[88:89], v[196:197]
	global_store_dwordx4 v[174:175], v[196:199], off offset:576
	s_nop 0
	global_load_dwordx4 v[196:199], v[180:181], off offset:512
	s_waitcnt vmcnt(14)
	v_pk_fma_f32 v[206:207], v[132:133], v[110:111], v[206:207]
	v_pk_fma_f32 v[204:205], v[130:131], v[108:109], v[204:205]
	global_store_dwordx4 v[176:177], v[204:207], off
	s_nop 0
	global_load_dwordx4 v[204:207], v[180:181], off offset:576
	s_waitcnt vmcnt(15)
	v_pk_fma_f32 v[210:211], v[122:123], v[106:107], v[210:211]
	v_pk_fma_f32 v[208:209], v[120:121], v[104:105], v[208:209]
	global_store_dwordx4 v[176:177], v[208:211], off offset:64
	s_nop 0
	v_lshl_add_u64 v[174:175], v[168:169], 0, v[156:157]
	global_load_dwordx4 v[208:211], v[174:175], off
	s_waitcnt vmcnt(16)
	v_pk_fma_f32 v[214:215], v[118:119], v[102:103], v[214:215]
	v_pk_fma_f32 v[212:213], v[116:117], v[100:101], v[212:213]
	global_store_dwordx4 v[176:177], v[212:215], off offset:512
	s_nop 0
	global_load_dwordx4 v[212:215], v[174:175], off offset:64
	s_waitcnt vmcnt(17)
	v_pk_fma_f32 v[218:219], v[114:115], v[90:91], v[218:219]
	v_pk_fma_f32 v[216:217], v[112:113], v[88:89], v[216:217]
	global_store_dwordx4 v[176:177], v[216:219], off offset:576
	s_nop 0
	global_load_dwordx4 v[216:219], v[174:175], off offset:512
	s_waitcnt vmcnt(18)
	v_pk_fma_f32 v[222:223], v[98:99], v[110:111], v[222:223]
	v_pk_fma_f32 v[220:221], v[96:97], v[108:109], v[220:221]
	global_store_dwordx4 v[178:179], v[220:223], off
	s_nop 0
	global_load_dwordx4 v[220:223], v[174:175], off offset:576
	s_waitcnt vmcnt(19)
	v_pk_fma_f32 v[226:227], v[94:95], v[106:107], v[226:227]
	v_pk_fma_f32 v[224:225], v[92:93], v[104:105], v[224:225]
	global_store_dwordx4 v[178:179], v[224:227], off offset:64
	s_nop 0
	v_lshl_add_u64 v[176:177], v[168:169], 0, v[158:159]
	global_load_dwordx4 v[224:227], v[176:177], off
	s_waitcnt vmcnt(20)
	v_pk_fma_f32 v[230:231], v[86:87], v[102:103], v[230:231]
	v_pk_fma_f32 v[228:229], v[84:85], v[100:101], v[228:229]
	global_store_dwordx4 v[178:179], v[228:231], off offset:512
	s_nop 0
	global_load_dwordx4 v[228:231], v[176:177], off offset:64
	s_waitcnt vmcnt(20)
	v_pk_fma_f32 v[186:187], v[78:79], v[90:91], v[186:187]
	v_pk_fma_f32 v[184:185], v[76:77], v[88:89], v[184:185]
	global_store_dwordx4 v[178:179], v[184:187], off offset:576
	s_nop 0
	global_load_dwordx4 v[184:187], v[176:177], off offset:512
	s_waitcnt vmcnt(20)
;     __device__ __forceinline__ void operator()(const pg8::f32x4 (&acc)[2][2][4][2], const pg8::Unit& u, int wr, int wc, int fr, int fq) const {
;     ...
;         for (int ai = 0; ai < 2; ++ai)
; #pragma unroll
;             for (int m = 0; m < 4; ++m) {
;                 float* rowp = base + (size_t)(ai * 128 + wr * 64 + m * 16 + fr) * DM + col0;
; #pragma unroll
;                 for (int bj = 0; bj < 2; ++bj)
; #pragma unroll
;                     for (int n = 0; n < 2; ++n) {
;                         pg8::f32x4* p = (pg8::f32x4*)(rowp + bj * 128 + n * 16);
;                         pg8::f32x4 xv = *p; xv = xv + gv[bj][n] * acc[ai][bj][m][n]; *p = xv;
;                     }
;                 if (m & 1) asm volatile("" ::: "memory");
;             }
	v_pk_fma_f32 v[190:191], v[82:83], v[110:111], v[190:191]
	v_pk_fma_f32 v[188:189], v[80:81], v[108:109], v[188:189]
	global_store_dwordx4 v[180:181], v[188:191], off
	s_nop 0
	global_load_dwordx4 v[188:191], v[176:177], off offset:576
	s_waitcnt vmcnt(20)
	v_pk_fma_f32 v[194:195], v[74:75], v[106:107], v[194:195]
	v_pk_fma_f32 v[192:193], v[72:73], v[104:105], v[192:193]
	global_store_dwordx4 v[180:181], v[192:195], off offset:64
	s_nop 0
	v_lshl_add_u64 v[178:179], v[168:169], 0, v[160:161]
	global_load_dwordx4 v[192:195], v[178:179], off
	s_waitcnt vmcnt(20)
	v_pk_fma_f32 v[198:199], v[70:71], v[102:103], v[198:199]
	v_pk_fma_f32 v[196:197], v[68:69], v[100:101], v[196:197]
	global_store_dwordx4 v[180:181], v[196:199], off offset:512
	s_nop 0
	global_load_dwordx4 v[196:199], v[178:179], off offset:64
	s_waitcnt vmcnt(20)
	v_pk_fma_f32 v[206:207], v[66:67], v[90:91], v[206:207]
	v_pk_fma_f32 v[204:205], v[64:65], v[88:89], v[204:205]
	global_store_dwordx4 v[180:181], v[204:207], off offset:576
	s_nop 0
	global_load_dwordx4 v[204:207], v[178:179], off offset:512
	s_waitcnt vmcnt(20)
	v_pk_fma_f32 v[210:211], v[62:63], v[110:111], v[210:211]
	v_pk_fma_f32 v[208:209], v[60:61], v[108:109], v[208:209]
	global_store_dwordx4 v[174:175], v[208:211], off
	s_nop 0
	global_load_dwordx4 v[208:211], v[178:179], off offset:576
	s_waitcnt vmcnt(20)
	v_pk_fma_f32 v[214:215], v[58:59], v[106:107], v[214:215]
	v_pk_fma_f32 v[212:213], v[56:57], v[104:105], v[212:213]
	global_store_dwordx4 v[174:175], v[212:215], off offset:64
	s_nop 0
	v_lshl_add_u64 v[180:181], v[168:169], 0, v[162:163]
	global_load_dwordx4 v[212:215], v[180:181], off
	s_waitcnt vmcnt(20)
	v_pk_fma_f32 v[218:219], v[54:55], v[102:103], v[218:219]
	v_pk_fma_f32 v[216:217], v[52:53], v[100:101], v[216:217]
	global_store_dwordx4 v[174:175], v[216:219], off offset:512
	s_nop 0
	global_load_dwordx4 v[216:219], v[180:181], off offset:64
	s_waitcnt vmcnt(20)
	v_pk_fma_f32 v[222:223], v[46:47], v[90:91], v[222:223]
	v_pk_fma_f32 v[220:221], v[44:45], v[88:89], v[220:221]
	global_store_dwordx4 v[174:175], v[220:223], off offset:576
	s_nop 0
	global_load_dwordx4 v[220:223], v[180:181], off offset:512
	s_waitcnt vmcnt(20)
	v_pk_fma_f32 v[226:227], v[50:51], v[110:111], v[226:227]
	v_pk_fma_f32 v[224:225], v[48:49], v[108:109], v[224:225]
	global_store_dwordx4 v[176:177], v[224:227], off
	s_nop 0
	global_load_dwordx4 v[224:227], v[180:181], off offset:576
	s_waitcnt vmcnt(20)
	v_pk_fma_f32 v[230:231], v[42:43], v[106:107], v[230:231]
	v_pk_fma_f32 v[228:229], v[40:41], v[104:105], v[228:229]
	global_store_dwordx4 v[176:177], v[228:231], off offset:64
	s_waitcnt vmcnt(19)
	v_pk_fma_f32 v[186:187], v[38:39], v[102:103], v[186:187]
	v_pk_fma_f32 v[184:185], v[36:37], v[100:101], v[184:185]
	global_store_dwordx4 v[176:177], v[184:187], off offset:512
	s_waitcnt vmcnt(18)
	v_pk_fma_f32 v[190:191], v[34:35], v[90:91], v[190:191]
	v_pk_fma_f32 v[188:189], v[32:33], v[88:89], v[188:189]
	global_store_dwordx4 v[176:177], v[188:191], off offset:576
	s_waitcnt vmcnt(17)
	v_pk_fma_f32 v[194:195], v[30:31], v[110:111], v[194:195]
	v_pk_fma_f32 v[192:193], v[28:29], v[108:109], v[192:193]
	global_store_dwordx4 v[178:179], v[192:195], off
	s_waitcnt vmcnt(16)
	v_pk_fma_f32 v[198:199], v[26:27], v[106:107], v[198:199]
	v_pk_fma_f32 v[196:197], v[24:25], v[104:105], v[196:197]
	global_store_dwordx4 v[178:179], v[196:199], off offset:64
	s_waitcnt vmcnt(15)
	v_pk_fma_f32 v[206:207], v[22:23], v[102:103], v[206:207]
	v_pk_fma_f32 v[204:205], v[20:21], v[100:101], v[204:205]
	global_store_dwordx4 v[178:179], v[204:207], off offset:512
	s_waitcnt vmcnt(14)
	v_pk_fma_f32 v[210:211], v[14:15], v[90:91], v[210:211]
	v_pk_fma_f32 v[208:209], v[12:13], v[88:89], v[208:209]
	global_store_dwordx4 v[178:179], v[208:211], off offset:576
	s_waitcnt vmcnt(13)
	v_pk_fma_f32 v[214:215], v[18:19], v[110:111], v[214:215]
	v_pk_fma_f32 v[212:213], v[16:17], v[108:109], v[212:213]
	global_store_dwordx4 v[180:181], v[212:215], off
	s_waitcnt vmcnt(12)
	v_pk_fma_f32 v[218:219], v[10:11], v[106:107], v[218:219]
	v_pk_fma_f32 v[216:217], v[8:9], v[104:105], v[216:217]
	global_store_dwordx4 v[180:181], v[216:219], off offset:64
	s_waitcnt vmcnt(11)
	v_pk_fma_f32 v[222:223], v[6:7], v[102:103], v[222:223]
	v_pk_fma_f32 v[220:221], v[4:5], v[100:101], v[220:221]
	global_store_dwordx4 v[180:181], v[220:223], off offset:512
	s_waitcnt vmcnt(10)
	v_pk_fma_f32 v[226:227], v[2:3], v[90:91], v[226:227]
	v_pk_fma_f32 v[224:225], v[0:1], v[88:89], v[224:225]
	global_store_dwordx4 v[180:181], v[224:227], off offset:576
	s_cbranch_vccnz .LBB0_1085
	s_andn2_b64 vcc, exec, s[0:1]
	s_cbranch_vccnz .LBB0_1084
	s_barrier
	s_branch .LBB0_1084

;     __device__ __forceinline__ void operator()(const pg8::f32x4 (&acc)[2][2][4][2], const pg8::Unit& u, int wr, int wc, int fr, int fq) const {
;         const int b = u.pm / 9, j = u.pm - b * 9;
;         float* base = (j == 0) ? xc + (size_t)b * CTX * DM : out + ((size_t)b * SEQ + (size_t)(j - 1) * 256) * DM;
;         const float* g = gate + (size_t)((j == 0) ? 16 : b) * MODW;
;         const int col0 = u.pn * 256 + wc * 32 + 4 * fq;
;         pg8::f32x4 gv[2][2];
; #pragma unroll
;         for (int bj = 0; bj < 2; ++bj)
; #pragma unroll
;             for (int n = 0; n < 2; ++n) gv[bj][n] = *(const pg8::f32x4*)(g + col0 + bj * 128 + n * 16);
; #pragma unroll
;         for (int ai = 0; ai < 2; ++ai)
; #pragma unroll
;             for (int m = 0; m < 4; ++m) {
;                 float* rowp = base + (size_t)(ai * 128 + wr * 64 + m * 16 + fr) * DM + col0;
; #pragma unroll
;                 for (int bj = 0; bj < 2; ++bj)
; #pragma unroll
;                     for (int n = 0; n < 2; ++n) {
;                         pg8::f32x4* p = (pg8::f32x4*)(rowp + bj * 128 + n * 16);
;                         pg8::f32x4 xv = *p; xv = xv + gv[bj][n] * acc[ai][bj][m][n]; *p = xv;
;                     }
;                 if (m & 1) asm volatile("" ::: "memory");
;             }
.LBB0_1129:
	s_lshl_b64 s[12:13], s[56:57], 2
	v_lshl_or_b32 v88, s15, 8, v171
	s_add_u32 s12, s11, s12
	v_ashrrev_i32_e32 v89, 31, v88
	s_addc_u32 s13, s24, s13
	v_lshlrev_b64 v[168:169], 2, v[88:89]
	v_lshl_add_u64 v[88:89], s[12:13], 0, v[168:169]
	v_lshl_add_u64 v[168:169], s[48:49], 0, v[168:169]
	v_lshl_add_u64 v[178:179], v[168:169], 0, v[148:149]
	global_load_dwordx4 v[108:111], v[88:89], off
	global_load_dwordx4 v[104:107], v[88:89], off offset:64
	global_load_dwordx4 v[100:103], v[88:89], off offset:512
	s_nop 0
	global_load_dwordx4 v[88:91], v[88:89], off offset:576
	s_mov_b64 s[48:49], -1
	s_and_b64 vcc, exec, s[38:39]
	v_lshl_add_u64 v[174:175], v[168:169], 0, v[148:149]
	global_load_dwordx4 v[184:187], v[174:175], off
	global_load_dwordx4 v[188:191], v[174:175], off offset:64
	global_load_dwordx4 v[192:195], v[174:175], off offset:512
	global_load_dwordx4 v[196:199], v[174:175], off offset:576
	v_lshl_add_u64 v[176:177], v[168:169], 0, v[150:151]
	global_load_dwordx4 v[204:207], v[176:177], off
	global_load_dwordx4 v[208:211], v[176:177], off offset:64
	global_load_dwordx4 v[212:215], v[176:177], off offset:512
	global_load_dwordx4 v[216:219], v[176:177], off offset:576
	v_lshl_add_u64 v[178:179], v[168:169], 0, v[152:153]
	global_load_dwordx4 v[220:223], v[178:179], off
	global_load_dwordx4 v[224:227], v[178:179], off offset:64
	global_load_dwordx4 v[228:231], v[178:179], off offset:512
	s_waitcnt vmcnt(10)
	v_pk_fma_f32 v[186:187], v[144:145], v[110:111], v[186:187]
	v_pk_fma_f32 v[184:185], v[142:143], v[108:109], v[184:185]
	global_store_dwordx4 v[174:175], v[184:187], off
	s_nop 0
	global_load_dwordx4 v[184:187], v[178:179], off offset:576
	s_waitcnt vmcnt(11)
	v_pk_fma_f32 v[190:191], v[140:141], v[106:107], v[190:191]
	v_pk_fma_f32 v[188:189], v[138:139], v[104:105], v[188:189]
	global_store_dwordx4 v[174:175], v[188:191], off offset:64
	s_nop 0
	v_lshl_add_u64 v[180:181], v[168:169], 0, v[154:155]
	global_load_dwordx4 v[188:191], v[180:181], off
	s_waitcnt vmcnt(12)
	v_pk_fma_f32 v[194:195], v[136:137], v[102:103], v[194:195]
	v_pk_fma_f32 v[192:193], v[134:135], v[100:101], v[192:193]
	global_store_dwordx4 v[174:175], v[192:195], off offset:512
	s_nop 0
	global_load_dwordx4 v[192:195], v[180:181], off offset:64
	s_waitcnt vmcnt(13)
	v_pk_fma_f32 v[198:199], v[126:127], v[90:91], v[198:199]
	v_pk_fma_f32 v[196:197], v[124:125], v[88:89], v[196:197]
	global_store_dwordx4 v[174:175], v[196:199], off offset:576
	s_nop 0
	global_load_dwordx4 v[196:199], v[180:181], off offset:512
	s_waitcnt vmcnt(14)
	v_pk_fma_f32 v[206:207], v[132:133], v[110:111], v[206:207]
	v_pk_fma_f32 v[204:205], v[130:131], v[108:109], v[204:205]
	global_store_dwordx4 v[176:177], v[204:207], off
	s_nop 0
	global_load_dwordx4 v[204:207], v[180:181], off offset:576
	s_waitcnt vmcnt(15)
	v_pk_fma_f32 v[210:211], v[122:123], v[106:107], v[210:211]
	v_pk_fma_f32 v[208:209], v[120:121], v[104:105], v[208:209]
	global_store_dwordx4 v[176:177], v[208:211], off offset:64
	s_nop 0
	v_lshl_add_u64 v[174:175], v[168:169], 0, v[156:157]
	global_load_dwordx4 v[208:211], v[174:175], off
	s_waitcnt vmcnt(16)
	v_pk_fma_f32 v[214:215], v[118:119], v[102:103], v[214:215]
	v_pk_fma_f32 v[212:213], v[116:117], v[100:101], v[212:213]
	global_store_dwordx4 v[176:177], v[212:215], off offset:512
	s_nop 0
	global_load_dwordx4 v[212:215], v[174:175], off offset:64
	s_waitcnt vmcnt(17)
	v_pk_fma_f32 v[218:219], v[114:115], v[90:91], v[218:219]
	v_pk_fma_f32 v[216:217], v[112:113], v[88:89], v[216:217]
	global_store_dwordx4 v[176:177], v[216:219], off offset:576
	s_nop 0
	global_load_dwordx4 v[216:219], v[174:175], off offset:512
	s_waitcnt vmcnt(18)
	v_pk_fma_f32 v[222:223], v[98:99], v[110:111], v[222:223]
	v_pk_fma_f32 v[220:221], v[96:97], v[108:109], v[220:221]
	global_store_dwordx4 v[178:179], v[220:223], off
	s_nop 0
	global_load_dwordx4 v[220:223], v[174:175], off offset:576
	s_waitcnt vmcnt(19)
	v_pk_fma_f32 v[226:227], v[94:95], v[106:107], v[226:227]
	v_pk_fma_f32 v[224:225], v[92:93], v[104:105], v[224:225]
	global_store_dwordx4 v[178:179], v[224:227], off offset:64
	s_nop 0
	v_lshl_add_u64 v[176:177], v[168:169], 0, v[158:159]
	global_load_dwordx4 v[224:227], v[176:177], off
	s_waitcnt vmcnt(20)
	v_pk_fma_f32 v[230:231], v[86:87], v[102:103], v[230:231]
	v_pk_fma_f32 v[228:229], v[84:85], v[100:101], v[228:229]
	global_store_dwordx4 v[178:179], v[228:231], off offset:512
	s_nop 0
	global_load_dwordx4 v[228:231], v[176:177], off offset:64
	s_waitcnt vmcnt(20)
	v_pk_fma_f32 v[186:187], v[78:79], v[90:91], v[186:187]
	v_pk_fma_f32 v[184:185], v[76:77], v[88:89], v[184:185]
	global_store_dwordx4 v[178:179], v[184:187], off offset:576
	s_nop 0
	global_load_dwordx4 v[184:187], v[176:177], off offset:512
	s_waitcnt vmcnt(20)
;     __device__ __forceinline__ void operator()(const pg8::f32x4 (&acc)[2][2][4][2], const pg8::Unit& u, int wr, int wc, int fr, int fq) const {
;     ...
;         for (int ai = 0; ai < 2; ++ai)
; #pragma unroll
;             for (int m = 0; m < 4; ++m) {
;                 float* rowp = base + (size_t)(ai * 128 + wr * 64 + m * 16 + fr) * DM + col0;
; #pragma unroll
;                 for (int bj = 0; bj < 2; ++bj)
; #pragma unroll
;                     for (int n = 0; n < 2; ++n) {
;                         pg8::f32x4* p = (pg8::f32x4*)(rowp + bj * 128 + n * 16);
;                         pg8::f32x4 xv = *p; xv = xv + gv[bj][n] * acc[ai][bj][m][n]; *p = xv;
;                     }
;                 if (m & 1) asm volatile("" ::: "memory");
;             }
	v_pk_fma_f32 v[190:191], v[82:83], v[110:111], v[190:191]
	v_pk_fma_f32 v[188:189], v[80:81], v[108:109], v[188:189]
	global_store_dwordx4 v[180:181], v[188:191], off
	s_nop 0
	global_load_dwordx4 v[188:191], v[176:177], off offset:576
	s_waitcnt vmcnt(20)
	v_pk_fma_f32 v[194:195], v[74:75], v[106:107], v[194:195]
	v_pk_fma_f32 v[192:193], v[72:73], v[104:105], v[192:193]
	global_store_dwordx4 v[180:181], v[192:195], off offset:64
	s_nop 0
	v_lshl_add_u64 v[178:179], v[168:169], 0, v[160:161]
	global_load_dwordx4 v[192:195], v[178:179], off
	s_waitcnt vmcnt(20)
	v_pk_fma_f32 v[198:199], v[70:71], v[102:103], v[198:199]
	v_pk_fma_f32 v[196:197], v[68:69], v[100:101], v[196:197]
	global_store_dwordx4 v[180:181], v[196:199], off offset:512
	s_nop 0
	global_load_dwordx4 v[196:199], v[178:179], off offset:64
	s_waitcnt vmcnt(20)
	v_pk_fma_f32 v[206:207], v[66:67], v[90:91], v[206:207]
	v_pk_fma_f32 v[204:205], v[64:65], v[88:89], v[204:205]
	global_store_dwordx4 v[180:181], v[204:207], off offset:576
	s_nop 0
	global_load_dwordx4 v[204:207], v[178:179], off offset:512
	s_waitcnt vmcnt(20)
	v_pk_fma_f32 v[210:211], v[62:63], v[110:111], v[210:211]
	v_pk_fma_f32 v[208:209], v[60:61], v[108:109], v[208:209]
	global_store_dwordx4 v[174:175], v[208:211], off
	s_nop 0
	global_load_dwordx4 v[208:211], v[178:179], off offset:576
	s_waitcnt vmcnt(20)
	v_pk_fma_f32 v[214:215], v[58:59], v[106:107], v[214:215]
	v_pk_fma_f32 v[212:213], v[56:57], v[104:105], v[212:213]
	global_store_dwordx4 v[174:175], v[212:215], off offset:64
	s_nop 0
	v_lshl_add_u64 v[180:181], v[168:169], 0, v[162:163]
	global_load_dwordx4 v[212:215], v[180:181], off
	s_waitcnt vmcnt(20)
	v_pk_fma_f32 v[218:219], v[54:55], v[102:103], v[218:219]
	v_pk_fma_f32 v[216:217], v[52:53], v[100:101], v[216:217]
	global_store_dwordx4 v[174:175], v[216:219], off offset:512
	s_nop 0
	global_load_dwordx4 v[216:219], v[180:181], off offset:64
	s_waitcnt vmcnt(20)
	v_pk_fma_f32 v[222:223], v[46:47], v[90:91], v[222:223]
	v_pk_fma_f32 v[220:221], v[44:45], v[88:89], v[220:221]
	global_store_dwordx4 v[174:175], v[220:223], off offset:576
	s_nop 0
	global_load_dwordx4 v[220:223], v[180:181], off offset:512
	s_waitcnt vmcnt(20)
	v_pk_fma_f32 v[226:227], v[50:51], v[110:111], v[226:227]
	v_pk_fma_f32 v[224:225], v[48:49], v[108:109], v[224:225]
	global_store_dwordx4 v[176:177], v[224:227], off
	s_nop 0
	global_load_dwordx4 v[224:227], v[180:181], off offset:576
	s_waitcnt vmcnt(20)
	v_pk_fma_f32 v[230:231], v[42:43], v[106:107], v[230:231]
	v_pk_fma_f32 v[228:229], v[40:41], v[104:105], v[228:229]
	global_store_dwordx4 v[176:177], v[228:231], off offset:64
	s_waitcnt vmcnt(19)
	v_pk_fma_f32 v[186:187], v[38:39], v[102:103], v[186:187]
	v_pk_fma_f32 v[184:185], v[36:37], v[100:101], v[184:185]
	global_store_dwordx4 v[176:177], v[184:187], off offset:512
	s_waitcnt vmcnt(18)
	v_pk_fma_f32 v[190:191], v[34:35], v[90:91], v[190:191]
	v_pk_fma_f32 v[188:189], v[32:33], v[88:89], v[188:189]
	global_store_dwordx4 v[176:177], v[188:191], off offset:576
	s_waitcnt vmcnt(17)
	v_pk_fma_f32 v[194:195], v[30:31], v[110:111], v[194:195]
	v_pk_fma_f32 v[192:193], v[28:29], v[108:109], v[192:193]
	global_store_dwordx4 v[178:179], v[192:195], off
	s_waitcnt vmcnt(16)
	v_pk_fma_f32 v[198:199], v[26:27], v[106:107], v[198:199]
	v_pk_fma_f32 v[196:197], v[24:25], v[104:105], v[196:197]
	global_store_dwordx4 v[178:179], v[196:199], off offset:64
	s_waitcnt vmcnt(15)
	v_pk_fma_f32 v[206:207], v[22:23], v[102:103], v[206:207]
	v_pk_fma_f32 v[204:205], v[20:21], v[100:101], v[204:205]
	global_store_dwordx4 v[178:179], v[204:207], off offset:512
	s_waitcnt vmcnt(14)
	v_pk_fma_f32 v[210:211], v[14:15], v[90:91], v[210:211]
	v_pk_fma_f32 v[208:209], v[12:13], v[88:89], v[208:209]
	global_store_dwordx4 v[178:179], v[208:211], off offset:576
	s_waitcnt vmcnt(13)
	v_pk_fma_f32 v[214:215], v[18:19], v[110:111], v[214:215]
	v_pk_fma_f32 v[212:213], v[16:17], v[108:109], v[212:213]
	global_store_dwordx4 v[180:181], v[212:215], off
	s_waitcnt vmcnt(12)
	v_pk_fma_f32 v[218:219], v[10:11], v[106:107], v[218:219]
	v_pk_fma_f32 v[216:217], v[8:9], v[104:105], v[216:217]
	global_store_dwordx4 v[180:181], v[216:219], off offset:64
	s_waitcnt vmcnt(11)
	v_pk_fma_f32 v[222:223], v[6:7], v[102:103], v[222:223]
	v_pk_fma_f32 v[220:221], v[4:5], v[100:101], v[220:221]
	global_store_dwordx4 v[180:181], v[220:223], off offset:512
	s_waitcnt vmcnt(10)
	v_pk_fma_f32 v[226:227], v[2:3], v[90:91], v[226:227]
	v_pk_fma_f32 v[224:225], v[0:1], v[88:89], v[224:225]
	global_store_dwordx4 v[180:181], v[224:227], off offset:576
	s_cbranch_vccnz .LBB0_1111
	s_andn2_b64 vcc, exec, s[0:1]
	s_cbranch_vccnz .LBB0_1110
	s_barrier
	s_branch .LBB0_1110
